# GEMM main-loop heads aligned to 256 bytes, plus HID sc1 stores and phase-B rewrites
# baseline (speedup 1.0000x reference)
.LBB0_445:
	s_add_u32 s56, s62, 0xb0080
	s_addc_u32 s57, s63, 0
	s_add_u32 s62, s60, 0x100
	v_mov_b32_e32 v2, 0
	s_addc_u32 s63, s61, 0
	s_mov_b32 s84, -2
	s_waitcnt lgkmcnt(0)
	v_mov_b32_e32 v3, v2
	v_mov_b32_e32 v4, v2
	v_mov_b32_e32 v5, v2
	v_mov_b32_e32 v6, v2
	v_mov_b32_e32 v7, v2
	v_mov_b32_e32 v8, v2
	v_mov_b32_e32 v9, v2
	v_mov_b32_e32 v18, v2
	v_mov_b32_e32 v19, v2
	v_mov_b32_e32 v20, v2
	v_mov_b32_e32 v21, v2
	v_mov_b32_e32 v22, v2
	v_mov_b32_e32 v23, v2
	v_mov_b32_e32 v24, v2
	v_mov_b32_e32 v25, v2
	v_mov_b32_e32 v34, v2
	v_mov_b32_e32 v35, v2
	v_mov_b32_e32 v36, v2
	v_mov_b32_e32 v37, v2
	v_mov_b32_e32 v38, v2
	v_mov_b32_e32 v39, v2
	v_mov_b32_e32 v40, v2
	v_mov_b32_e32 v41, v2
	v_mov_b32_e32 v50, v2
	v_mov_b32_e32 v51, v2
	v_mov_b32_e32 v52, v2
	v_mov_b32_e32 v53, v2
	v_mov_b32_e32 v54, v2
	v_mov_b32_e32 v55, v2
	v_mov_b32_e32 v56, v2
	v_mov_b32_e32 v57, v2
	v_mov_b32_e32 v10, v2
	v_mov_b32_e32 v11, v2
	v_mov_b32_e32 v12, v2
	v_mov_b32_e32 v13, v2
	v_mov_b32_e32 v14, v2
	v_mov_b32_e32 v15, v2
	v_mov_b32_e32 v16, v2
	v_mov_b32_e32 v17, v2
	v_mov_b32_e32 v26, v2
	v_mov_b32_e32 v27, v2
	v_mov_b32_e32 v28, v2
	v_mov_b32_e32 v29, v2
	v_mov_b32_e32 v30, v2
	v_mov_b32_e32 v31, v2
	v_mov_b32_e32 v32, v2
	v_mov_b32_e32 v33, v2
	v_mov_b32_e32 v42, v2
	v_mov_b32_e32 v43, v2
	v_mov_b32_e32 v44, v2
	v_mov_b32_e32 v45, v2
	v_mov_b32_e32 v46, v2
	v_mov_b32_e32 v47, v2
	v_mov_b32_e32 v48, v2
	v_mov_b32_e32 v49, v2
	v_mov_b32_e32 v58, v2
	v_mov_b32_e32 v59, v2
	v_mov_b32_e32 v60, v2
	v_mov_b32_e32 v61, v2
	v_mov_b32_e32 v62, v2
	v_mov_b32_e32 v63, v2
	v_mov_b32_e32 v64, v2
	v_mov_b32_e32 v65, v2
	v_mov_b32_e32 v66, v2
	v_mov_b32_e32 v67, v2
	v_mov_b32_e32 v68, v2
	v_mov_b32_e32 v69, v2
	v_mov_b32_e32 v70, v2
	v_mov_b32_e32 v71, v2
	v_mov_b32_e32 v72, v2
	v_mov_b32_e32 v73, v2
	v_mov_b32_e32 v82, v2
	v_mov_b32_e32 v83, v2
	v_mov_b32_e32 v84, v2
	v_mov_b32_e32 v85, v2
	v_mov_b32_e32 v86, v2
	v_mov_b32_e32 v87, v2
	v_mov_b32_e32 v88, v2
	v_mov_b32_e32 v89, v2
	v_mov_b32_e32 v98, v2
	v_mov_b32_e32 v99, v2
	v_mov_b32_e32 v100, v2
	v_mov_b32_e32 v101, v2
	v_mov_b32_e32 v102, v2
	v_mov_b32_e32 v103, v2
	v_mov_b32_e32 v104, v2
	v_mov_b32_e32 v105, v2
	v_mov_b32_e32 v118, v2
	v_mov_b32_e32 v119, v2
	v_mov_b32_e32 v120, v2
	v_mov_b32_e32 v121, v2
	v_mov_b32_e32 v122, v2
	v_mov_b32_e32 v123, v2
	v_mov_b32_e32 v124, v2
	v_mov_b32_e32 v125, v2
	v_mov_b32_e32 v74, v2
	v_mov_b32_e32 v75, v2
	v_mov_b32_e32 v76, v2
	v_mov_b32_e32 v77, v2
	v_mov_b32_e32 v78, v2
	v_mov_b32_e32 v79, v2
	v_mov_b32_e32 v80, v2
	v_mov_b32_e32 v81, v2
	v_mov_b32_e32 v90, v2
	v_mov_b32_e32 v91, v2
	v_mov_b32_e32 v92, v2
	v_mov_b32_e32 v93, v2
	v_mov_b32_e32 v94, v2
	v_mov_b32_e32 v95, v2
	v_mov_b32_e32 v96, v2
	v_mov_b32_e32 v97, v2
	v_mov_b32_e32 v106, v2
	v_mov_b32_e32 v107, v2
	v_mov_b32_e32 v108, v2
	v_mov_b32_e32 v109, v2
	v_mov_b32_e32 v110, v2
	v_mov_b32_e32 v111, v2
	v_mov_b32_e32 v112, v2
	v_mov_b32_e32 v113, v2
	v_mov_b32_e32 v138, v2
	v_mov_b32_e32 v139, v2
	v_mov_b32_e32 v140, v2
	v_mov_b32_e32 v141, v2
	v_mov_b32_e32 v142, v2
	v_mov_b32_e32 v143, v2
	v_mov_b32_e32 v144, v2
	v_mov_b32_e32 v145, v2
	s_mov_b64 s[12:13], 0xb0000
	s_mov_b64 s[86:87], 0x108000
	s_mov_b64 s[96:97], 0x58080
	s_mov_b64 vcc, 0xb0080
	s_mov_b64 s[0:1], 0x108080
	.p2alignl 8, 3212836864

.LBB0_487:
	s_ashr_i32 s57, s56, 31
	s_lshl_b64 s[20:21], s[56:57], 19
	s_add_u32 s60, s94, s20
	s_addc_u32 s61, s95, s21
	s_and_b64 s[20:21], s[54:55], exec
	s_cselect_b32 s57, s61, s69
	s_cselect_b32 s86, s60, s68
	s_ashr_i32 s51, s50, 31
	s_lshl_b64 s[20:21], s[50:51], 19
	s_add_u32 s62, s15, s20
	s_addc_u32 s63, s42, s21
	s_and_b64 s[20:21], s[54:55], exec
	s_cselect_b32 s51, s63, s77
	s_cselect_b32 s87, s62, s76
	s_add_u32 s68, s68, 0x40080
	s_addc_u32 s69, s69, 0
	s_add_u32 s91, s76, 0x100
	v_mov_b32_e32 v2, 0
	s_addc_u32 s96, s77, 0
	s_mov_b32 s97, -2
	v_mov_b32_e32 v3, v2
	v_mov_b32_e32 v4, v2
	v_mov_b32_e32 v5, v2
	v_mov_b32_e32 v10, v2
	v_mov_b32_e32 v11, v2
	v_mov_b32_e32 v12, v2
	v_mov_b32_e32 v13, v2
	v_mov_b32_e32 v22, v2
	v_mov_b32_e32 v23, v2
	v_mov_b32_e32 v24, v2
	v_mov_b32_e32 v25, v2
	v_mov_b32_e32 v26, v2
	v_mov_b32_e32 v27, v2
	v_mov_b32_e32 v28, v2
	v_mov_b32_e32 v29, v2
	v_mov_b32_e32 v38, v2
	v_mov_b32_e32 v39, v2
	v_mov_b32_e32 v40, v2
	v_mov_b32_e32 v41, v2
	v_mov_b32_e32 v42, v2
	v_mov_b32_e32 v43, v2
	v_mov_b32_e32 v44, v2
	v_mov_b32_e32 v45, v2
	v_mov_b32_e32 v54, v2
	v_mov_b32_e32 v55, v2
	v_mov_b32_e32 v56, v2
	v_mov_b32_e32 v57, v2
	v_mov_b32_e32 v58, v2
	v_mov_b32_e32 v59, v2
	v_mov_b32_e32 v60, v2
	v_mov_b32_e32 v61, v2
	v_mov_b32_e32 v6, v2
	v_mov_b32_e32 v7, v2
	v_mov_b32_e32 v8, v2
	v_mov_b32_e32 v9, v2
	v_mov_b32_e32 v14, v2
	v_mov_b32_e32 v15, v2
	v_mov_b32_e32 v16, v2
	v_mov_b32_e32 v17, v2
	v_mov_b32_e32 v18, v2
	v_mov_b32_e32 v19, v2
	v_mov_b32_e32 v20, v2
	v_mov_b32_e32 v21, v2
	v_mov_b32_e32 v30, v2
	v_mov_b32_e32 v31, v2
	v_mov_b32_e32 v32, v2
	v_mov_b32_e32 v33, v2
	v_mov_b32_e32 v34, v2
	v_mov_b32_e32 v35, v2
	v_mov_b32_e32 v36, v2
	v_mov_b32_e32 v37, v2
	v_mov_b32_e32 v46, v2
	v_mov_b32_e32 v47, v2
	v_mov_b32_e32 v48, v2
	v_mov_b32_e32 v49, v2
	v_mov_b32_e32 v50, v2
	v_mov_b32_e32 v51, v2
	v_mov_b32_e32 v52, v2
	v_mov_b32_e32 v53, v2
	v_mov_b32_e32 v62, v2
	v_mov_b32_e32 v63, v2
	v_mov_b32_e32 v64, v2
	v_mov_b32_e32 v65, v2
	v_mov_b32_e32 v70, v2
	v_mov_b32_e32 v71, v2
	v_mov_b32_e32 v72, v2
	v_mov_b32_e32 v73, v2
	v_mov_b32_e32 v74, v2
	v_mov_b32_e32 v75, v2
	v_mov_b32_e32 v76, v2
	v_mov_b32_e32 v77, v2
	v_mov_b32_e32 v86, v2
	v_mov_b32_e32 v87, v2
	v_mov_b32_e32 v88, v2
	v_mov_b32_e32 v89, v2
	v_mov_b32_e32 v90, v2
	v_mov_b32_e32 v91, v2
	v_mov_b32_e32 v92, v2
	v_mov_b32_e32 v93, v2
	v_mov_b32_e32 v102, v2
	v_mov_b32_e32 v103, v2
	v_mov_b32_e32 v104, v2
	v_mov_b32_e32 v105, v2
	v_mov_b32_e32 v106, v2
	v_mov_b32_e32 v107, v2
	v_mov_b32_e32 v108, v2
	v_mov_b32_e32 v109, v2
	v_mov_b32_e32 v118, v2
	v_mov_b32_e32 v119, v2
	v_mov_b32_e32 v120, v2
	v_mov_b32_e32 v121, v2
	v_mov_b32_e32 v122, v2
	v_mov_b32_e32 v123, v2
	v_mov_b32_e32 v124, v2
	v_mov_b32_e32 v125, v2
	v_mov_b32_e32 v66, v2
	v_mov_b32_e32 v67, v2
	v_mov_b32_e32 v68, v2
	v_mov_b32_e32 v69, v2
	v_mov_b32_e32 v78, v2
	v_mov_b32_e32 v79, v2
	v_mov_b32_e32 v80, v2
	v_mov_b32_e32 v81, v2
	v_mov_b32_e32 v82, v2
	v_mov_b32_e32 v83, v2
	v_mov_b32_e32 v84, v2
	v_mov_b32_e32 v85, v2
	v_mov_b32_e32 v94, v2
	v_mov_b32_e32 v95, v2
	v_mov_b32_e32 v96, v2
	v_mov_b32_e32 v97, v2
	v_mov_b32_e32 v98, v2
	v_mov_b32_e32 v99, v2
	v_mov_b32_e32 v100, v2
	v_mov_b32_e32 v101, v2
	v_mov_b32_e32 v110, v2
	v_mov_b32_e32 v111, v2
	v_mov_b32_e32 v112, v2
	v_mov_b32_e32 v113, v2
	v_mov_b32_e32 v114, v2
	v_mov_b32_e32 v115, v2
	v_mov_b32_e32 v116, v2
	v_mov_b32_e32 v117, v2
	v_mov_b32_e32 v126, v2
	v_mov_b32_e32 v127, v2
	v_mov_b32_e32 v128, v2
	v_mov_b32_e32 v129, v2
	.p2alignl 8, 3212836864

.LBB0_561:
	s_ashr_i32 s51, s50, 31
	s_lshl_b64 s[56:57], s[50:51], 19
	s_add_u32 s56, s15, s56
	s_addc_u32 s57, s42, s57
	s_and_b64 s[60:61], s[54:55], exec
	s_cselect_b32 s51, s57, s63
	s_cselect_b32 s86, s56, s62
	s_ashr_i32 s49, s48, 31
	s_lshl_b64 s[60:61], s[48:49], 19
	s_add_u32 s60, s43, s60
	s_addc_u32 s61, s46, s61
	s_and_b64 s[76:77], s[54:55], exec
	s_cselect_b32 s49, s61, s69
	s_cselect_b32 s87, s60, s68
	s_lshl_b32 s20, s20, 11
	s_and_b32 s20, s20, 0x1800
	s_waitcnt lgkmcnt(0)
	v_mov_b32_e32 v2, v1
	v_mov_b32_e32 v3, v1
	s_add_u32 s97, s68, 0x100
	v_mov_b32_e32 v0, v1
	v_mov_b64_e32 v[6:7], v[2:3]
	v_mov_b64_e32 v[10:11], v[2:3]
	v_mov_b64_e32 v[22:23], v[2:3]
	v_mov_b64_e32 v[26:27], v[2:3]
	v_mov_b64_e32 v[38:39], v[2:3]
	v_mov_b64_e32 v[42:43], v[2:3]
	v_mov_b64_e32 v[54:55], v[2:3]
	v_mov_b64_e32 v[58:59], v[2:3]
	v_mov_b64_e32 v[14:15], v[2:3]
	v_mov_b64_e32 v[18:19], v[2:3]
	v_mov_b64_e32 v[30:31], v[2:3]
	v_mov_b64_e32 v[34:35], v[2:3]
	v_mov_b64_e32 v[46:47], v[2:3]
	v_mov_b64_e32 v[50:51], v[2:3]
	v_mov_b64_e32 v[62:63], v[2:3]
	v_mov_b64_e32 v[66:67], v[2:3]
	v_mov_b64_e32 v[70:71], v[2:3]
	v_mov_b64_e32 v[74:75], v[2:3]
	v_mov_b64_e32 v[86:87], v[2:3]
	v_mov_b64_e32 v[90:91], v[2:3]
	v_mov_b64_e32 v[102:103], v[2:3]
	v_mov_b64_e32 v[106:107], v[2:3]
	v_mov_b64_e32 v[130:131], v[2:3]
	v_mov_b64_e32 v[138:139], v[2:3]
	v_mov_b64_e32 v[78:79], v[2:3]
	v_mov_b64_e32 v[82:83], v[2:3]
	v_mov_b64_e32 v[94:95], v[2:3]
	v_mov_b64_e32 v[98:99], v[2:3]
	v_mov_b64_e32 v[110:111], v[2:3]
	v_mov_b64_e32 v[114:115], v[2:3]
	v_mov_b64_e32 v[142:143], v[2:3]
	v_mov_b64_e32 v[146:147], v[2:3]
	v_add_u32_e32 v219, s20, v216
	v_lshl_add_u64 v[116:117], s[62:63], 0, v[186:187]
	s_addc_u32 vcc_lo, s69, 0
	s_mov_b32 vcc_hi, -2
	s_mov_b64 s[68:69], 0
	v_mov_b64_e32 v[4:5], v[0:1]
	v_mov_b64_e32 v[8:9], v[0:1]
	v_mov_b64_e32 v[20:21], v[0:1]
	v_mov_b64_e32 v[24:25], v[0:1]
	v_mov_b64_e32 v[36:37], v[0:1]
	v_mov_b64_e32 v[40:41], v[0:1]
	v_mov_b64_e32 v[52:53], v[0:1]
	v_mov_b64_e32 v[56:57], v[0:1]
	v_mov_b64_e32 v[12:13], v[0:1]
	v_mov_b64_e32 v[16:17], v[0:1]
	v_mov_b64_e32 v[28:29], v[0:1]
	v_mov_b64_e32 v[32:33], v[0:1]
	v_mov_b64_e32 v[44:45], v[0:1]
	v_mov_b64_e32 v[48:49], v[0:1]
	v_mov_b64_e32 v[60:61], v[0:1]
	v_mov_b64_e32 v[64:65], v[0:1]
	v_mov_b64_e32 v[68:69], v[0:1]
	v_mov_b64_e32 v[72:73], v[0:1]
	v_mov_b64_e32 v[84:85], v[0:1]
	v_mov_b64_e32 v[88:89], v[0:1]
	v_mov_b64_e32 v[100:101], v[0:1]
	v_mov_b64_e32 v[104:105], v[0:1]
	v_mov_b64_e32 v[128:129], v[0:1]
	v_mov_b64_e32 v[136:137], v[0:1]
	v_mov_b64_e32 v[76:77], v[0:1]
	v_mov_b64_e32 v[80:81], v[0:1]
	v_mov_b64_e32 v[92:93], v[0:1]
	v_mov_b64_e32 v[96:97], v[0:1]
	v_mov_b64_e32 v[108:109], v[0:1]
	v_mov_b64_e32 v[112:113], v[0:1]
	v_mov_b64_e32 v[140:141], v[0:1]
	v_mov_b64_e32 v[144:145], v[0:1]
	s_branch .LBB0_563
	.p2alignl 8, 3212836864

.LBB0_603:
	s_ashr_i32 s51, s50, 31
	s_lshl_b64 s[20:21], s[50:51], 18
	s_add_u32 s78, s0, s20
	s_addc_u32 s79, s1, s21
	s_and_b64 s[20:21], s[56:57], exec
	s_cselect_b32 s42, s79, s7
	s_cselect_b32 s43, s78, s6
	s_ashr_i32 s49, s48, 31
	s_lshl_b64 s[20:21], s[48:49], 18
	s_add_u32 s40, s76, s20
	s_addc_u32 s41, s77, s21
	s_and_b64 s[20:21], s[56:57], exec
	s_cselect_b32 s46, s41, s69
	s_cselect_b32 s47, s40, s68
	s_add_u32 s6, s6, 0x20080
	s_addc_u32 s7, s7, 0
	s_add_u32 s49, s68, 0x100
	v_mov_b32_e32 v2, 0
	s_addc_u32 s51, s69, 0
	s_mov_b32 s84, -2
	s_waitcnt lgkmcnt(0)
	v_mov_b32_e32 v3, v2
	v_mov_b32_e32 v4, v2
	v_mov_b32_e32 v5, v2
	v_mov_b32_e32 v6, v2
	v_mov_b32_e32 v7, v2
	v_mov_b32_e32 v8, v2
	v_mov_b32_e32 v9, v2
	v_mov_b32_e32 v18, v2
	v_mov_b32_e32 v19, v2
	v_mov_b32_e32 v20, v2
	v_mov_b32_e32 v21, v2
	v_mov_b32_e32 v22, v2
	v_mov_b32_e32 v23, v2
	v_mov_b32_e32 v24, v2
	v_mov_b32_e32 v25, v2
	v_mov_b32_e32 v34, v2
	v_mov_b32_e32 v35, v2
	v_mov_b32_e32 v36, v2
	v_mov_b32_e32 v37, v2
	v_mov_b32_e32 v38, v2
	v_mov_b32_e32 v39, v2
	v_mov_b32_e32 v40, v2
	v_mov_b32_e32 v41, v2
	v_mov_b32_e32 v50, v2
	v_mov_b32_e32 v51, v2
	v_mov_b32_e32 v52, v2
	v_mov_b32_e32 v53, v2
	v_mov_b32_e32 v54, v2
	v_mov_b32_e32 v55, v2
	v_mov_b32_e32 v56, v2
	v_mov_b32_e32 v57, v2
	v_mov_b32_e32 v10, v2
	v_mov_b32_e32 v11, v2
	v_mov_b32_e32 v12, v2
	v_mov_b32_e32 v13, v2
	v_mov_b32_e32 v14, v2
	v_mov_b32_e32 v15, v2
	v_mov_b32_e32 v16, v2
	v_mov_b32_e32 v17, v2
	v_mov_b32_e32 v26, v2
	v_mov_b32_e32 v27, v2
	v_mov_b32_e32 v28, v2
	v_mov_b32_e32 v29, v2
	v_mov_b32_e32 v30, v2
	v_mov_b32_e32 v31, v2
	v_mov_b32_e32 v32, v2
	v_mov_b32_e32 v33, v2
	v_mov_b32_e32 v42, v2
	v_mov_b32_e32 v43, v2
	v_mov_b32_e32 v44, v2
	v_mov_b32_e32 v45, v2
	v_mov_b32_e32 v46, v2
	v_mov_b32_e32 v47, v2
	v_mov_b32_e32 v48, v2
	v_mov_b32_e32 v49, v2
	v_mov_b32_e32 v58, v2
	v_mov_b32_e32 v59, v2
	v_mov_b32_e32 v60, v2
	v_mov_b32_e32 v61, v2
	v_mov_b32_e32 v62, v2
	v_mov_b32_e32 v63, v2
	v_mov_b32_e32 v64, v2
	v_mov_b32_e32 v65, v2
	v_mov_b32_e32 v66, v2
	v_mov_b32_e32 v67, v2
	v_mov_b32_e32 v68, v2
	v_mov_b32_e32 v69, v2
	v_mov_b32_e32 v70, v2
	v_mov_b32_e32 v71, v2
	v_mov_b32_e32 v72, v2
	v_mov_b32_e32 v73, v2
	v_mov_b32_e32 v82, v2
	v_mov_b32_e32 v83, v2
	v_mov_b32_e32 v84, v2
	v_mov_b32_e32 v85, v2
	v_mov_b32_e32 v86, v2
	v_mov_b32_e32 v87, v2
	v_mov_b32_e32 v88, v2
	v_mov_b32_e32 v89, v2
	v_mov_b32_e32 v98, v2
	v_mov_b32_e32 v99, v2
	v_mov_b32_e32 v100, v2
	v_mov_b32_e32 v101, v2
	v_mov_b32_e32 v102, v2
	v_mov_b32_e32 v103, v2
	v_mov_b32_e32 v104, v2
	v_mov_b32_e32 v105, v2
	v_mov_b32_e32 v114, v2
	v_mov_b32_e32 v115, v2
	v_mov_b32_e32 v116, v2
	v_mov_b32_e32 v117, v2
	v_mov_b32_e32 v118, v2
	v_mov_b32_e32 v119, v2
	v_mov_b32_e32 v120, v2
	v_mov_b32_e32 v121, v2
	v_mov_b32_e32 v74, v2
	v_mov_b32_e32 v75, v2
	v_mov_b32_e32 v76, v2
	v_mov_b32_e32 v77, v2
	v_mov_b32_e32 v78, v2
	v_mov_b32_e32 v79, v2
	v_mov_b32_e32 v80, v2
	v_mov_b32_e32 v81, v2
	v_mov_b32_e32 v90, v2
	v_mov_b32_e32 v91, v2
	v_mov_b32_e32 v92, v2
	v_mov_b32_e32 v93, v2
	v_mov_b32_e32 v94, v2
	v_mov_b32_e32 v95, v2
	v_mov_b32_e32 v96, v2
	v_mov_b32_e32 v97, v2
	v_mov_b32_e32 v106, v2
	v_mov_b32_e32 v107, v2
	v_mov_b32_e32 v108, v2
	v_mov_b32_e32 v109, v2
	v_mov_b32_e32 v110, v2
	v_mov_b32_e32 v111, v2
	v_mov_b32_e32 v112, v2
	v_mov_b32_e32 v113, v2
	v_mov_b32_e32 v122, v2
	v_mov_b32_e32 v123, v2
	v_mov_b32_e32 v124, v2
	v_mov_b32_e32 v125, v2
	v_mov_b32_e32 v126, v2
	v_mov_b32_e32 v127, v2
	v_mov_b32_e32 v128, v2
	v_mov_b32_e32 v129, v2
	.p2alignl 8, 3212836864

.LBB0_777:
	s_ashr_i32 s61, s60, 31
	s_lshl_b64 s[20:21], s[60:61], 19
	s_add_u32 s62, s94, s20
	s_addc_u32 s63, s95, s21
	s_and_b64 s[20:21], s[56:57], exec
	s_cselect_b32 s61, s63, s77
	s_cselect_b32 s85, s62, s76
	s_ashr_i32 s59, s58, 31
	s_lshl_b64 s[20:21], s[58:59], 19
	s_add_u32 s68, s15, s20
	s_addc_u32 s69, s42, s21
	s_and_b64 s[20:21], s[56:57], exec
	s_cselect_b32 s59, s69, s79
	s_cselect_b32 s86, s68, s78
	s_add_u32 s76, s76, 0x40080
	s_addc_u32 s77, s77, 0
	s_add_u32 s87, s78, 0x100
	v_mov_b32_e32 v2, 0
	s_addc_u32 vcc_lo, s79, 0
	s_mov_b32 vcc_hi, -2
	s_waitcnt lgkmcnt(0)
	v_mov_b32_e32 v3, v2
	v_mov_b32_e32 v4, v2
	v_mov_b32_e32 v5, v2
	v_mov_b32_e32 v6, v2
	v_mov_b32_e32 v7, v2
	v_mov_b32_e32 v8, v2
	v_mov_b32_e32 v9, v2
	v_mov_b32_e32 v18, v2
	v_mov_b32_e32 v19, v2
	v_mov_b32_e32 v20, v2
	v_mov_b32_e32 v21, v2
	v_mov_b32_e32 v22, v2
	v_mov_b32_e32 v23, v2
	v_mov_b32_e32 v24, v2
	v_mov_b32_e32 v25, v2
	v_mov_b32_e32 v34, v2
	v_mov_b32_e32 v35, v2
	v_mov_b32_e32 v36, v2
	v_mov_b32_e32 v37, v2
	v_mov_b32_e32 v38, v2
	v_mov_b32_e32 v39, v2
	v_mov_b32_e32 v40, v2
	v_mov_b32_e32 v41, v2
	v_mov_b32_e32 v50, v2
	v_mov_b32_e32 v51, v2
	v_mov_b32_e32 v52, v2
	v_mov_b32_e32 v53, v2
	v_mov_b32_e32 v54, v2
	v_mov_b32_e32 v55, v2
	v_mov_b32_e32 v56, v2
	v_mov_b32_e32 v57, v2
	v_mov_b32_e32 v10, v2
	v_mov_b32_e32 v11, v2
	v_mov_b32_e32 v12, v2
	v_mov_b32_e32 v13, v2
	v_mov_b32_e32 v14, v2
	v_mov_b32_e32 v15, v2
	v_mov_b32_e32 v16, v2
	v_mov_b32_e32 v17, v2
	v_mov_b32_e32 v26, v2
	v_mov_b32_e32 v27, v2
	v_mov_b32_e32 v28, v2
	v_mov_b32_e32 v29, v2
	v_mov_b32_e32 v30, v2
	v_mov_b32_e32 v31, v2
	v_mov_b32_e32 v32, v2
	v_mov_b32_e32 v33, v2
	v_mov_b32_e32 v42, v2
	v_mov_b32_e32 v43, v2
	v_mov_b32_e32 v44, v2
	v_mov_b32_e32 v45, v2
	v_mov_b32_e32 v46, v2
	v_mov_b32_e32 v47, v2
	v_mov_b32_e32 v48, v2
	v_mov_b32_e32 v49, v2
	v_mov_b32_e32 v58, v2
	v_mov_b32_e32 v59, v2
	v_mov_b32_e32 v60, v2
	v_mov_b32_e32 v61, v2
	v_mov_b32_e32 v62, v2
	v_mov_b32_e32 v63, v2
	v_mov_b32_e32 v64, v2
	v_mov_b32_e32 v65, v2
	v_mov_b32_e32 v66, v2
	v_mov_b32_e32 v67, v2
	v_mov_b32_e32 v68, v2
	v_mov_b32_e32 v69, v2
	v_mov_b32_e32 v70, v2
	v_mov_b32_e32 v71, v2
	v_mov_b32_e32 v72, v2
	v_mov_b32_e32 v73, v2
	v_mov_b32_e32 v82, v2
	v_mov_b32_e32 v83, v2
	v_mov_b32_e32 v84, v2
	v_mov_b32_e32 v85, v2
	v_mov_b32_e32 v86, v2
	v_mov_b32_e32 v87, v2
	v_mov_b32_e32 v88, v2
	v_mov_b32_e32 v89, v2
	v_mov_b32_e32 v98, v2
	v_mov_b32_e32 v99, v2
	v_mov_b32_e32 v100, v2
	v_mov_b32_e32 v101, v2
	v_mov_b32_e32 v102, v2
	v_mov_b32_e32 v103, v2
	v_mov_b32_e32 v104, v2
	v_mov_b32_e32 v105, v2
	v_mov_b32_e32 v114, v2
	v_mov_b32_e32 v115, v2
	v_mov_b32_e32 v116, v2
	v_mov_b32_e32 v117, v2
	v_mov_b32_e32 v118, v2
	v_mov_b32_e32 v119, v2
	v_mov_b32_e32 v120, v2
	v_mov_b32_e32 v121, v2
	v_mov_b32_e32 v74, v2
	v_mov_b32_e32 v75, v2
	v_mov_b32_e32 v76, v2
	v_mov_b32_e32 v77, v2
	v_mov_b32_e32 v78, v2
	v_mov_b32_e32 v79, v2
	v_mov_b32_e32 v80, v2
	v_mov_b32_e32 v81, v2
	v_mov_b32_e32 v90, v2
	v_mov_b32_e32 v91, v2
	v_mov_b32_e32 v92, v2
	v_mov_b32_e32 v93, v2
	v_mov_b32_e32 v94, v2
	v_mov_b32_e32 v95, v2
	v_mov_b32_e32 v96, v2
	v_mov_b32_e32 v97, v2
	v_mov_b32_e32 v106, v2
	v_mov_b32_e32 v107, v2
	v_mov_b32_e32 v108, v2
	v_mov_b32_e32 v109, v2
	v_mov_b32_e32 v110, v2
	v_mov_b32_e32 v111, v2
	v_mov_b32_e32 v112, v2
	v_mov_b32_e32 v113, v2
	v_mov_b32_e32 v122, v2
	v_mov_b32_e32 v123, v2
	v_mov_b32_e32 v124, v2
	v_mov_b32_e32 v125, v2
	v_mov_b32_e32 v126, v2
	v_mov_b32_e32 v127, v2
	v_mov_b32_e32 v128, v2
	v_mov_b32_e32 v129, v2
	.p2alignl 8, 3212836864

.LBB0_849:
	s_ashr_i32 s79, s78, 31
	s_lshl_b64 s[20:21], s[78:79], 19
	s_add_u32 s88, s4, s20
	s_addc_u32 s89, s5, s21
	s_and_b64 s[20:21], s[54:55], exec
	s_cselect_b32 s76, s89, s57
	s_cselect_b32 s77, s88, s56
	s_ashr_i32 s69, s68, 31
	s_lshl_b64 s[20:21], s[68:69], 19
	v_readlane_b32 s12, v247, 42
	s_add_u32 s94, s12, s20
	v_readlane_b32 s12, v245, 61
	s_addc_u32 s95, s12, s21
	s_and_b64 s[20:21], s[54:55], exec
	s_cselect_b32 s69, s95, s59
	s_cselect_b32 s79, s94, s58
	s_add_u32 s56, s56, 0x40080
	s_addc_u32 s57, s57, 0
	s_add_u32 s86, s58, 0x100
	v_mov_b32_e32 v2, 0
	s_addc_u32 s87, s59, 0
	s_mov_b32 s91, -2
	v_mov_b32_e32 v3, v2
	v_mov_b32_e32 v4, v2
	v_mov_b32_e32 v5, v2
	v_mov_b32_e32 v6, v2
	v_mov_b32_e32 v7, v2
	v_mov_b32_e32 v8, v2
	v_mov_b32_e32 v9, v2
	v_mov_b32_e32 v18, v2
	v_mov_b32_e32 v19, v2
	v_mov_b32_e32 v20, v2
	v_mov_b32_e32 v21, v2
	v_mov_b32_e32 v22, v2
	v_mov_b32_e32 v23, v2
	v_mov_b32_e32 v24, v2
	v_mov_b32_e32 v25, v2
	v_mov_b32_e32 v34, v2
	v_mov_b32_e32 v35, v2
	v_mov_b32_e32 v36, v2
	v_mov_b32_e32 v37, v2
	v_mov_b32_e32 v38, v2
	v_mov_b32_e32 v39, v2
	v_mov_b32_e32 v40, v2
	v_mov_b32_e32 v41, v2
	v_mov_b32_e32 v50, v2
	v_mov_b32_e32 v51, v2
	v_mov_b32_e32 v52, v2
	v_mov_b32_e32 v53, v2
	v_mov_b32_e32 v54, v2
	v_mov_b32_e32 v55, v2
	v_mov_b32_e32 v56, v2
	v_mov_b32_e32 v57, v2
	v_mov_b32_e32 v10, v2
	v_mov_b32_e32 v11, v2
	v_mov_b32_e32 v12, v2
	v_mov_b32_e32 v13, v2
	v_mov_b32_e32 v14, v2
	v_mov_b32_e32 v15, v2
	v_mov_b32_e32 v16, v2
	v_mov_b32_e32 v17, v2
	v_mov_b32_e32 v26, v2
	v_mov_b32_e32 v27, v2
	v_mov_b32_e32 v28, v2
	v_mov_b32_e32 v29, v2
	v_mov_b32_e32 v30, v2
	v_mov_b32_e32 v31, v2
	v_mov_b32_e32 v32, v2
	v_mov_b32_e32 v33, v2
	v_mov_b32_e32 v42, v2
	v_mov_b32_e32 v43, v2
	v_mov_b32_e32 v44, v2
	v_mov_b32_e32 v45, v2
	v_mov_b32_e32 v46, v2
	v_mov_b32_e32 v47, v2
	v_mov_b32_e32 v48, v2
	v_mov_b32_e32 v49, v2
	v_mov_b32_e32 v58, v2
	v_mov_b32_e32 v59, v2
	v_mov_b32_e32 v60, v2
	v_mov_b32_e32 v61, v2
	v_mov_b32_e32 v62, v2
	v_mov_b32_e32 v63, v2
	v_mov_b32_e32 v64, v2
	v_mov_b32_e32 v65, v2
	v_mov_b32_e32 v66, v2
	v_mov_b32_e32 v67, v2
	v_mov_b32_e32 v68, v2
	v_mov_b32_e32 v69, v2
	v_mov_b32_e32 v70, v2
	v_mov_b32_e32 v71, v2
	v_mov_b32_e32 v72, v2
	v_mov_b32_e32 v73, v2
	v_mov_b32_e32 v82, v2
	v_mov_b32_e32 v83, v2
	v_mov_b32_e32 v84, v2
	v_mov_b32_e32 v85, v2
	v_mov_b32_e32 v86, v2
	v_mov_b32_e32 v87, v2
	v_mov_b32_e32 v88, v2
	v_mov_b32_e32 v89, v2
	v_mov_b32_e32 v98, v2
	v_mov_b32_e32 v99, v2
	v_mov_b32_e32 v100, v2
	v_mov_b32_e32 v101, v2
	v_mov_b32_e32 v102, v2
	v_mov_b32_e32 v103, v2
	v_mov_b32_e32 v104, v2
	v_mov_b32_e32 v105, v2
	v_mov_b32_e32 v114, v2
	v_mov_b32_e32 v115, v2
	v_mov_b32_e32 v116, v2
	v_mov_b32_e32 v117, v2
	v_mov_b32_e32 v118, v2
	v_mov_b32_e32 v119, v2
	v_mov_b32_e32 v120, v2
	v_mov_b32_e32 v121, v2
	v_mov_b32_e32 v74, v2
	v_mov_b32_e32 v75, v2
	v_mov_b32_e32 v76, v2
	v_mov_b32_e32 v77, v2
	v_mov_b32_e32 v78, v2
	v_mov_b32_e32 v79, v2
	v_mov_b32_e32 v80, v2
	v_mov_b32_e32 v81, v2
	v_mov_b32_e32 v90, v2
	v_mov_b32_e32 v91, v2
	v_mov_b32_e32 v92, v2
	v_mov_b32_e32 v93, v2
	v_mov_b32_e32 v94, v2
	v_mov_b32_e32 v95, v2
	v_mov_b32_e32 v96, v2
	v_mov_b32_e32 v97, v2
	v_mov_b32_e32 v106, v2
	v_mov_b32_e32 v107, v2
	v_mov_b32_e32 v108, v2
	v_mov_b32_e32 v109, v2
	v_mov_b32_e32 v110, v2
	v_mov_b32_e32 v111, v2
	v_mov_b32_e32 v112, v2
	v_mov_b32_e32 v113, v2
	v_mov_b32_e32 v122, v2
	v_mov_b32_e32 v123, v2
	v_mov_b32_e32 v124, v2
	v_mov_b32_e32 v125, v2
	v_mov_b32_e32 v126, v2
	v_mov_b32_e32 v127, v2
	v_mov_b32_e32 v128, v2
	v_mov_b32_e32 v129, v2
	.p2alignl 8, 3212836864

.LBB0_1051:
	s_ashr_i32 s41, s40, 31
	s_lshl_b64 s[20:21], s[40:41], 17
	s_add_u32 s50, s14, s20
	s_addc_u32 s51, s15, s21
	s_and_b64 s[20:21], s[52:53], exec
	s_cselect_b32 s41, s51, s59
	s_cselect_b32 s86, s50, s58
	s_ashr_i32 s49, s48, 31
	s_lshl_b64 s[20:21], s[48:49], 17
	s_add_u32 s54, s42, s20
	s_addc_u32 s55, s43, s21
	s_and_b64 s[20:21], s[52:53], exec
	v_mov_b32_e32 v2, 0
	s_cselect_b32 s49, s55, s57
	s_cselect_b32 s87, s54, s56
	s_mov_b64 s[68:69], 0
	s_mov_b64 s[60:61], -1
	s_mov_b64 s[62:63], 0
	v_mov_b32_e32 v3, v2
	v_mov_b32_e32 v4, v2
	v_mov_b32_e32 v5, v2
	v_mov_b32_e32 v6, v2
	v_mov_b32_e32 v7, v2
	v_mov_b32_e32 v8, v2
	v_mov_b32_e32 v9, v2
	v_mov_b32_e32 v10, v2
	v_mov_b32_e32 v11, v2
	v_mov_b32_e32 v12, v2
	v_mov_b32_e32 v13, v2
	v_mov_b32_e32 v18, v2
	v_mov_b32_e32 v19, v2
	v_mov_b32_e32 v20, v2
	v_mov_b32_e32 v21, v2
	v_mov_b32_e32 v26, v2
	v_mov_b32_e32 v27, v2
	v_mov_b32_e32 v28, v2
	v_mov_b32_e32 v29, v2
	v_mov_b32_e32 v34, v2
	v_mov_b32_e32 v35, v2
	v_mov_b32_e32 v36, v2
	v_mov_b32_e32 v37, v2
	v_mov_b32_e32 v42, v2
	v_mov_b32_e32 v43, v2
	v_mov_b32_e32 v44, v2
	v_mov_b32_e32 v45, v2
	v_mov_b32_e32 v50, v2
	v_mov_b32_e32 v51, v2
	v_mov_b32_e32 v52, v2
	v_mov_b32_e32 v53, v2
	v_mov_b32_e32 v14, v2
	v_mov_b32_e32 v15, v2
	v_mov_b32_e32 v16, v2
	v_mov_b32_e32 v17, v2
	v_mov_b32_e32 v22, v2
	v_mov_b32_e32 v23, v2
	v_mov_b32_e32 v24, v2
	v_mov_b32_e32 v25, v2
	v_mov_b32_e32 v30, v2
	v_mov_b32_e32 v31, v2
	v_mov_b32_e32 v32, v2
	v_mov_b32_e32 v33, v2
	v_mov_b32_e32 v38, v2
	v_mov_b32_e32 v39, v2
	v_mov_b32_e32 v40, v2
	v_mov_b32_e32 v41, v2
	v_mov_b32_e32 v46, v2
	v_mov_b32_e32 v47, v2
	v_mov_b32_e32 v48, v2
	v_mov_b32_e32 v49, v2
	v_mov_b32_e32 v54, v2
	v_mov_b32_e32 v55, v2
	v_mov_b32_e32 v56, v2
	v_mov_b32_e32 v57, v2
	v_mov_b32_e32 v58, v2
	v_mov_b32_e32 v59, v2
	v_mov_b32_e32 v60, v2
	v_mov_b32_e32 v61, v2
	v_mov_b32_e32 v62, v2
	v_mov_b32_e32 v63, v2
	v_mov_b32_e32 v64, v2
	v_mov_b32_e32 v65, v2
	v_mov_b32_e32 v66, v2
	v_mov_b32_e32 v67, v2
	v_mov_b32_e32 v68, v2
	v_mov_b32_e32 v69, v2
	v_mov_b32_e32 v70, v2
	v_mov_b32_e32 v71, v2
	v_mov_b32_e32 v72, v2
	v_mov_b32_e32 v73, v2
	v_mov_b32_e32 v74, v2
	v_mov_b32_e32 v75, v2
	v_mov_b32_e32 v76, v2
	v_mov_b32_e32 v77, v2
	v_mov_b32_e32 v82, v2
	v_mov_b32_e32 v83, v2
	v_mov_b32_e32 v84, v2
	v_mov_b32_e32 v85, v2
	v_mov_b32_e32 v90, v2
	v_mov_b32_e32 v91, v2
	v_mov_b32_e32 v92, v2
	v_mov_b32_e32 v93, v2
	v_mov_b32_e32 v98, v2
	v_mov_b32_e32 v99, v2
	v_mov_b32_e32 v100, v2
	v_mov_b32_e32 v101, v2
	v_mov_b32_e32 v106, v2
	v_mov_b32_e32 v107, v2
	v_mov_b32_e32 v108, v2
	v_mov_b32_e32 v109, v2
	v_mov_b32_e32 v114, v2
	v_mov_b32_e32 v115, v2
	v_mov_b32_e32 v116, v2
	v_mov_b32_e32 v117, v2
	v_mov_b32_e32 v78, v2
	v_mov_b32_e32 v79, v2
	v_mov_b32_e32 v80, v2
	v_mov_b32_e32 v81, v2
	v_mov_b32_e32 v86, v2
	v_mov_b32_e32 v87, v2
	v_mov_b32_e32 v88, v2
	v_mov_b32_e32 v89, v2
	v_mov_b32_e32 v94, v2
	v_mov_b32_e32 v95, v2
	v_mov_b32_e32 v96, v2
	v_mov_b32_e32 v97, v2
	v_mov_b32_e32 v102, v2
	v_mov_b32_e32 v103, v2
	v_mov_b32_e32 v104, v2
	v_mov_b32_e32 v105, v2
	v_mov_b32_e32 v110, v2
	v_mov_b32_e32 v111, v2
	v_mov_b32_e32 v112, v2
	v_mov_b32_e32 v113, v2
	v_mov_b32_e32 v118, v2
	v_mov_b32_e32 v119, v2
	v_mov_b32_e32 v120, v2
	v_mov_b32_e32 v121, v2
	v_mov_b32_e32 v122, v2
	v_mov_b32_e32 v123, v2
	v_mov_b32_e32 v124, v2
	v_mov_b32_e32 v125, v2
	v_mov_b32_e32 v126, v2
	v_mov_b32_e32 v127, v2
	v_mov_b32_e32 v128, v2
	v_mov_b32_e32 v129, v2
	.p2alignl 8, 3212836864
